# attention loop: staging loads issued one iteration earlier, one wait per two fragments
# speedup vs baseline: 1.0221x; 1.0032x over previous
; __device__ __forceinline__ void att_qk(const LAS unsigned char* Kb, const bf16x8 (&qf)[2][2], int nst, int j, int qpos, float slope2, int fr, int fq, f32x4 (&sc)[2][4]) {
;     constexpr int KSTR = 272;
; #pragma unroll
;     for (int st = 0; st < 4; ++st) {
;         if (st < nst) {
;             const float d0 = (float)(qpos - (64 * j + 16 * st + 4 * fq));
;             f32x4 s0;
; #pragma unroll
;             for (int e = 0; e < 4; ++e) s0[e] = -slope2 * __builtin_fabsf(d0 - (float)e) - 12.0f;
;             f32x4 s1 = s0;
; #pragma unroll
;             for (int ks = 0; ks < 2; ++ks) {
;                 const bf16x8 k0 = *(const LAS bf16x8*)(Kb + (16 * st + fr) * KSTR + (32 * ks + 8 * fq) * 2);
;                 const bf16x8 k1 = *(const LAS bf16x8*)(Kb + (16 * st + fr) * KSTR + (64 + 32 * ks + 8 * fq) * 2);
;                 s0 = __builtin_amdgcn_mfma_f32_16x16x32_bf16(k0, qf[0][ks], s0, 0, 0, 0);
;                 s1 = __builtin_amdgcn_mfma_f32_16x16x32_bf16(k1, qf[1][ks], s1, 0, 0, 0);
;             }
;             sc[0][st] = s0; sc[1][st] = s1;
;         }
;     }
; }
; __device__ __forceinline__ void att_pv(const LAS unsigned char* Vb, int nst, const f32x4 (&sc)[2][4], f32x4 (&O)[2][8], float& l0, float& l1, int fr, int fq) {
;     constexpr int VSTR = 144;
;     if (nst <= 0) return;
;     unsigned pw[2][4][2];
; #pragma unroll
;     for (int st = 0; st < 4; ++st) {
;         if (st < nst) {
;             float p0[4], p1[4];
; #pragma unroll
;             for (int e = 0; e < 4; ++e) { p0[e] = __builtin_amdgcn_exp2f(sc[0][st][e]); p1[e] = __builtin_amdgcn_exp2f(sc[1][st][e]); l0 += p0[e]; l1 += p1[e]; }
;             pw[0][st][0] = pk2(p0[0], p0[1]); pw[0][st][1] = pk2(p0[2], p0[3]); pw[1][st][0] = pk2(p1[0], p1[1]); pw[1][st][1] = pk2(p1[2], p1[3]);
;         } else { pw[0][st][0] = 0u; pw[0][st][1] = 0u; pw[1][st][0] = 0u; pw[1][st][1] = 0u; }
;     }
; #pragma unroll
;     for (int ks2 = 0; ks2 < 2; ++ks2) {
;         if (ks2 == 0 || nst == 4) {
;             const u32x4 a0 = (u32x4){pw[0][2 * ks2][0], pw[0][2 * ks2][1], pw[0][2 * ks2 + 1][0], pw[0][2 * ks2 + 1][1]};
;             const u32x4 a1 = (u32x4){pw[1][2 * ks2][0], pw[1][2 * ks2][1], pw[1][2 * ks2 + 1][0], pw[1][2 * ks2 + 1][1]};
;             const bf16x8 pf0 = __builtin_bit_cast(bf16x8, a0), pf1 = __builtin_bit_cast(bf16x8, a1);
; #pragma unroll
.LBB0_619:
	s_add_i32 s0, s6, 16
	s_lshl_b32 s0, s0, 10
	s_lshl_b32 s1, s34, 1
	s_add_u32 s22, s10, s0
	s_addc_u32 s23, s11, 0
	s_add_u32 s22, s22, s1
	s_addc_u32 s23, s23, 0
	s_bfe_u32 s0, s17, 0x50003
	s_mul_i32 s0, s0, 0x84000
	s_add_u32 s24, s86, 0xb700000
	s_addc_u32 s25, s87, 0
	s_add_u32 s24, s24, s0
	s_addc_u32 s25, s25, 0
	s_mov_b32 s18, 0xc6ea6000
	s_xor_b32 s19, s20, 0x80000000
	s_movk_i32 s46, 0x1080
	s_mov_b32 s4, 0
	v_and_b32_e32 v46, 3, v209
	v_lshlrev_b32_e32 v46, 4, v46
	v_mad_u32_u24 v46, v240, s46, v46
	v_add_u32_e32 v47, s31, v249
	v_add_u32_e32 v47, 16, v47
	v_cvt_f32_i32_e32 v47, v47
	v_add_f32_e32 v47, 0xc2800000, v47
	v_mov_b32_e32 v236, 0
	v_mov_b32_e32 v237, 0
	s_mov_b32 s5, 1
	s_cmp_le_u32 s5, s37
	s_cselect_b32 s45, s16, s18
	s_add_i32 s0, s37, 1
	s_cmp_le_u32 s5, s0
	s_cselect_b32 s43, s16, s18
	v_mov_b32_e32 v4, s43
	v_fma_f32 v48, |v47|, s19, v4
	v_subrev_f32_e32 v49, 0x3f800000, v47
	v_fma_f32 v49, |v49|, s19, v4
	v_subrev_f32_e32 v50, 0x40000000, v47
	v_fma_f32 v50, |v50|, s19, v4
	v_subrev_f32_e32 v51, 0x40400000, v47
	v_fma_f32 v51, |v51|, s19, v4
	v_mov_b32_e32 v4, s45
	v_subrev_f32_e32 v52, 0x41800000, v47
	v_fma_f32 v52, |v52|, s19, v4
	v_subrev_f32_e32 v53, 0x41880000, v47
	v_fma_f32 v53, |v53|, s19, v4
	v_subrev_f32_e32 v54, 0x41900000, v47
	v_fma_f32 v54, |v54|, s19, v4
	v_subrev_f32_e32 v55, 0x41980000, v47
	v_fma_f32 v55, |v55|, s19, v4
	v_subrev_f32_e32 v56, 0x42000000, v47
	v_fma_f32 v56, |v56|, s19, v4
	v_subrev_f32_e32 v57, 0x42040000, v47
	v_fma_f32 v57, |v57|, s19, v4
	v_subrev_f32_e32 v58, 0x42080000, v47
	v_fma_f32 v58, |v58|, s19, v4
	v_subrev_f32_e32 v59, 0x420c0000, v47
	v_fma_f32 v59, |v59|, s19, v4
	v_subrev_f32_e32 v60, 0x42400000, v47
	v_fma_f32 v60, |v60|, s19, v4
	v_subrev_f32_e32 v61, 0x42440000, v47
	v_fma_f32 v61, |v61|, s19, v4
	v_subrev_f32_e32 v62, 0x42480000, v47
	v_fma_f32 v62, |v62|, s19, v4
	v_subrev_f32_e32 v63, 0x424c0000, v47
	v_fma_f32 v63, |v63|, s19, v4
	v_add_f32_e32 v47, 0xc2800000, v47
	s_sub_i32 s1, s36, 1
	s_add_i32 s0, s4, 2
	s_min_u32 s0, s0, s1
	s_add_i32 s5, s4, 1
	s_min_u32 s5, s5, s1
	s_lshl_b32 s0, s0, 6
	s_lshl_b32 s5, s5, 7
	v_add_u32_e32 v223, s0, v243
	v_min_u32_e32 v223, 0x7ff, v223
	v_lshl_add_u32 v223, v223, 10, v224
	s_add_u32 s26, s24, s5
	s_addc_u32 s27, s25, 0
	global_load_dwordx4 v[84:87], v223, s[22:23]
	global_load_dwordx4 v[88:91], v223, s[22:23] offset:128
	global_load_dwordx4 v[92:95], v46, s[26:27]
	global_load_dwordx4 v[96:99], v46, s[26:27] offset:64
.Latt_top:
	s_add_i32 s0, s4, 1
	s_cmp_ge_u32 s0, s36
	s_cbranch_scc1 .Latt_it_l
.Latt_it_e:
	ds_read_b128 v[6:9], v253 offset:17536
	ds_read_b128 v[10:13], v253 offset:17408
	ds_read_b128 v[14:17], v253 offset:21888
	ds_read_b128 v[18:21], v253 offset:21760
	ds_read_b128 v[22:25], v253 offset:26240
	ds_read_b128 v[26:29], v253 offset:26112
	ds_read_b128 v[30:33], v253 offset:30592
	ds_read_b128 v[34:37], v253 offset:30464
	v_exp_f32_e32 v152, v152
	v_exp_f32_e32 v153, v153
	v_exp_f32_e32 v154, v154
	v_exp_f32_e32 v155, v155
	v_exp_f32_e32 v156, v156
	v_exp_f32_e32 v157, v157
	v_exp_f32_e32 v158, v158
	v_exp_f32_e32 v159, v159
	v_exp_f32_e32 v168, v168
	v_exp_f32_e32 v169, v169
	v_exp_f32_e32 v170, v170
	v_exp_f32_e32 v171, v171
	v_exp_f32_e32 v172, v172
	v_exp_f32_e32 v173, v173
	v_exp_f32_e32 v174, v174
	v_exp_f32_e32 v175, v175
	v_cvt_pk_bf16_f32 v38, v152, v153
	v_cvt_pk_bf16_f32 v39, v154, v155
	v_cvt_pk_bf16_f32 v42, v156, v157
	v_cvt_pk_bf16_f32 v43, v158, v159
	v_pk_add_f32 v[234:235], v[234:235], v[152:153]
	v_pk_add_f32 v[234:235], v[234:235], v[154:155]
	v_pk_add_f32 v[236:237], v[236:237], v[156:157]
	v_pk_add_f32 v[236:237], v[236:237], v[158:159]
	v_cvt_pk_bf16_f32 v40, v168, v169
	v_cvt_pk_bf16_f32 v41, v170, v171
	v_cvt_pk_bf16_f32 v44, v172, v173
	v_cvt_pk_bf16_f32 v45, v174, v175
	v_pk_add_f32 v[234:235], v[234:235], v[168:169]
	v_pk_add_f32 v[234:235], v[234:235], v[170:171]
	v_pk_add_f32 v[236:237], v[236:237], v[172:173]
	v_pk_add_f32 v[236:237], v[236:237], v[174:175]
	s_waitcnt lgkmcnt(6)
	v_mfma_f32_16x16x32_bf16 v[64:67], v[6:9], v[112:115], v[48:51]
	ds_read_b128 v[6:9], v253 offset:17600
	v_exp_f32_e32 v192, v192
	v_exp_f32_e32 v193, v193
	v_mfma_f32_16x16x32_bf16 v[48:51], v[10:13], v[80:83], v[48:51]
	ds_read_b128 v[10:13], v253 offset:17472
	v_exp_f32_e32 v194, v194
	v_exp_f32_e32 v195, v195
	s_waitcnt lgkmcnt(6)
	v_mfma_f32_16x16x32_bf16 v[68:71], v[14:17], v[112:115], v[52:55]
	ds_read_b128 v[14:17], v253 offset:21952
	v_exp_f32_e32 v196, v196
	v_exp_f32_e32 v197, v197
	v_mfma_f32_16x16x32_bf16 v[52:55], v[18:21], v[80:83], v[52:55]
	ds_read_b128 v[18:21], v253 offset:21824
	v_exp_f32_e32 v198, v198
	v_exp_f32_e32 v199, v199
	s_waitcnt lgkmcnt(6)
	v_mfma_f32_16x16x32_bf16 v[72:75], v[22:25], v[112:115], v[56:59]
	ds_read_b128 v[22:25], v253 offset:26304
	v_exp_f32_e32 v200, v200
	v_exp_f32_e32 v201, v201
	v_mfma_f32_16x16x32_bf16 v[56:59], v[26:29], v[80:83], v[56:59]
	ds_read_b128 v[26:29], v253 offset:26176
	v_exp_f32_e32 v202, v202
	v_exp_f32_e32 v203, v203
	s_waitcnt lgkmcnt(6)
	v_mfma_f32_16x16x32_bf16 v[76:79], v[30:33], v[112:115], v[60:63]
	ds_read_b128 v[30:33], v253 offset:30656
	v_exp_f32_e32 v204, v204
	v_exp_f32_e32 v205, v205
	v_mfma_f32_16x16x32_bf16 v[60:63], v[34:37], v[80:83], v[60:63]
	ds_read_b128 v[34:37], v253 offset:30528
	v_exp_f32_e32 v206, v206
	v_exp_f32_e32 v207, v207
	s_waitcnt lgkmcnt(6)
	v_mfma_f32_16x16x32_bf16 v[64:67], v[6:9], v[128:131], v[64:67]
	ds_read_b64 v[6:7], v245 offset:34816
	ds_read_b64 v[8:9], v245 offset:34848
	v_cvt_pk_bf16_f32 v0, v192, v193
	v_cvt_pk_bf16_f32 v1, v194, v195
	v_mfma_f32_16x16x32_bf16 v[48:51], v[10:13], v[104:107], v[48:51]
	ds_read_b64 v[10:11], v245 offset:37120
	ds_read_b64 v[12:13], v245 offset:37152
	v_cvt_pk_bf16_f32 v230, v196, v197
	v_cvt_pk_bf16_f32 v231, v198, v199
	s_waitcnt lgkmcnt(8)
; __device__ __forceinline__ void att_pv(const LAS unsigned char* Vb, int nst, const f32x4 (&sc)[2][4], f32x4 (&O)[2][8], float& l0, float& l1, int fr, int fq) {
;     constexpr int VSTR = 144;
;     if (nst <= 0) return;
;     unsigned pw[2][4][2];
; #pragma unroll
;     for (int st = 0; st < 4; ++st) {
;         if (st < nst) {
;             float p0[4], p1[4];
; #pragma unroll
;             for (int e = 0; e < 4; ++e) { p0[e] = __builtin_amdgcn_exp2f(sc[0][st][e]); p1[e] = __builtin_amdgcn_exp2f(sc[1][st][e]); l0 += p0[e]; l1 += p1[e]; }
;             pw[0][st][0] = pk2(p0[0], p0[1]); pw[0][st][1] = pk2(p0[2], p0[3]); pw[1][st][0] = pk2(p1[0], p1[1]); pw[1][st][1] = pk2(p1[2], p1[3]);
;         } else { pw[0][st][0] = 0u; pw[0][st][1] = 0u; pw[1][st][0] = 0u; pw[1][st][1] = 0u; }
;     }
; #pragma unroll
;     for (int ks2 = 0; ks2 < 2; ++ks2) {
;         if (ks2 == 0 || nst == 4) {
;             const u32x4 a0 = (u32x4){pw[0][2 * ks2][0], pw[0][2 * ks2][1], pw[0][2 * ks2 + 1][0], pw[0][2 * ks2 + 1][1]};
;             const u32x4 a1 = (u32x4){pw[1][2 * ks2][0], pw[1][2 * ks2][1], pw[1][2 * ks2 + 1][0], pw[1][2 * ks2 + 1][1]};
;             const bf16x8 pf0 = __builtin_bit_cast(bf16x8, a0), pf1 = __builtin_bit_cast(bf16x8, a1);
; #pragma unroll
;             for (int dt = 0; dt < 8; ++dt) {
;                 const LAS unsigned char* vp = Vb + (16 * dt + fr) * VSTR + (32 * ks2 + 4 * fq) * 2;
;                 const u32x2 va = *(const LAS u32x2*)vp, vb2 = *(const LAS u32x2*)(vp + 32);
;                 const bf16x8 vf = __builtin_bit_cast(bf16x8, (u32x4){va.x, va.y, vb2.x, vb2.y});
;                 O[0][dt] = __builtin_amdgcn_mfma_f32_16x16x32_bf16(vf, pf0, O[0][dt], 0, 0, 0);
;                 O[1][dt] = __builtin_amdgcn_mfma_f32_16x16x32_bf16(vf, pf1, O[1][dt], 0, 0, 0);
;             }
;         }
;     }
; }
; __device__ __forceinline__ void attn_phase(const Params& P, LAS unsigned char* lds, int tid, int wid, int lane) {
;     ...
;             if (j + 1 < nt) { if (j + 2 < nt) ATT_LOADK(a, j + 2); ATT_LOADV(a, j + 1); }
;             if (j + 1 < nt) att_qk(lds + KBUF, qf, ATT_NST(j + 1), j + 1, qpos, slope2, fr, fq, scB);
;             att_pv(lds + VOFF, ATT_NST(j), scA, O, l0, l1, fr, fq);
;             if (j + 1 < nt) { if (j + 2 < nt) ATT_WRITEK(a, 0); ATT_WRITEV(a, 1); }
;             ATT_BAR();
;             if (j + 1 >= nt) break;
	v_mfma_f32_16x16x32_bf16 v[68:71], v[14:17], v[128:131], v[68:71]
	ds_read_b64 v[14:15], v245 offset:39424
	ds_read_b64 v[16:17], v245 offset:39456
	v_pk_add_f32 v[234:235], v[234:235], v[192:193]
	v_pk_add_f32 v[234:235], v[234:235], v[194:195]
	v_mfma_f32_16x16x32_bf16 v[52:55], v[18:21], v[104:107], v[52:55]
	ds_read_b64 v[18:19], v245 offset:41728
	ds_read_b64 v[20:21], v245 offset:41760
	v_pk_add_f32 v[236:237], v[236:237], v[196:197]
	v_pk_add_f32 v[236:237], v[236:237], v[198:199]
	s_waitcnt lgkmcnt(10)
	v_mfma_f32_16x16x32_bf16 v[72:75], v[22:25], v[128:131], v[72:75]
	ds_read_b64 v[22:23], v245 offset:44032
	ds_read_b64 v[24:25], v245 offset:44064
	v_cvt_pk_bf16_f32 v2, v200, v201
	v_cvt_pk_bf16_f32 v3, v202, v203
	v_mfma_f32_16x16x32_bf16 v[56:59], v[26:29], v[104:107], v[56:59]
	ds_read_b64 v[26:27], v245 offset:46336
	ds_read_b64 v[28:29], v245 offset:46368
	v_cvt_pk_bf16_f32 v232, v204, v205
	v_cvt_pk_bf16_f32 v233, v206, v207
	s_waitcnt lgkmcnt(12)
	v_mfma_f32_16x16x32_bf16 v[76:79], v[30:33], v[128:131], v[76:79]
	ds_read_b64 v[30:31], v245 offset:48640
	ds_read_b64 v[32:33], v245 offset:48672
	v_pk_add_f32 v[234:235], v[234:235], v[200:201]
	v_pk_add_f32 v[234:235], v[234:235], v[202:203]
	v_mfma_f32_16x16x32_bf16 v[60:63], v[34:37], v[104:107], v[60:63]
	ds_read_b64 v[34:35], v245 offset:50944
	ds_read_b64 v[36:37], v245 offset:50976
	v_pk_add_f32 v[236:237], v[236:237], v[204:205]
	v_pk_add_f32 v[236:237], v[236:237], v[206:207]
	s_add_i32 s5, s4, 2
	s_cmp_le_u32 s5, s37
	s_cselect_b32 s45, s16, s18
	s_add_i32 s0, s37, 1
	s_cmp_le_u32 s5, s0
	s_cselect_b32 s43, s16, s18
	s_waitcnt lgkmcnt(12)
	v_mfma_f32_16x16x32_bf16 v[184:187], v[6:9], v[38:41], v[184:187]
	v_mov_b32_e32 v4, s43
	v_fma_f32 v152, |v47|, s19, v4
	v_subrev_f32_e32 v153, 0x3f800000, v47
	v_mfma_f32_16x16x32_bf16 v[188:191], v[6:9], v[42:45], v[188:191]
	ds_read_b64 v[6:7], v245 offset:34880
	ds_read_b64 v[8:9], v245 offset:34912
	v_fma_f32 v153, |v153|, s19, v4
	v_subrev_f32_e32 v154, 0x40000000, v47
	v_fma_f32 v154, |v154|, s19, v4
	v_mfma_f32_16x16x32_bf16 v[180:183], v[10:13], v[38:41], v[180:183]
	v_subrev_f32_e32 v155, 0x40400000, v47
	v_fma_f32 v155, |v155|, s19, v4
	v_mfma_f32_16x16x32_bf16 v[176:179], v[10:13], v[42:45], v[176:179]
	ds_read_b64 v[10:11], v245 offset:37184
	ds_read_b64 v[12:13], v245 offset:37216
	v_mov_b32_e32 v4, s45
	v_subrev_f32_e32 v168, 0x41800000, v47
	s_waitcnt lgkmcnt(12)
	v_mfma_f32_16x16x32_bf16 v[164:167], v[14:17], v[38:41], v[164:167]
	v_fma_f32 v168, |v168|, s19, v4
	v_subrev_f32_e32 v169, 0x41880000, v47
	v_mfma_f32_16x16x32_bf16 v[160:163], v[14:17], v[42:45], v[160:163]
	ds_read_b64 v[14:15], v245 offset:39488
	ds_read_b64 v[16:17], v245 offset:39520
	v_fma_f32 v169, |v169|, s19, v4
	v_subrev_f32_e32 v170, 0x41900000, v47
	v_mfma_f32_16x16x32_bf16 v[148:151], v[18:21], v[38:41], v[148:151]
	v_fma_f32 v170, |v170|, s19, v4
	v_subrev_f32_e32 v171, 0x41980000, v47
	v_mfma_f32_16x16x32_bf16 v[144:147], v[18:21], v[42:45], v[144:147]
	ds_read_b64 v[18:19], v245 offset:41792
	ds_read_b64 v[20:21], v245 offset:41824
	v_fma_f32 v171, |v171|, s19, v4
	v_subrev_f32_e32 v192, 0x42000000, v47
	s_waitcnt lgkmcnt(12)
	v_mfma_f32_16x16x32_bf16 v[140:143], v[22:25], v[38:41], v[140:143]
	v_fma_f32 v192, |v192|, s19, v4
	v_subrev_f32_e32 v193, 0x42040000, v47
	v_mfma_f32_16x16x32_bf16 v[136:139], v[22:25], v[42:45], v[136:139]
	ds_read_b64 v[22:23], v245 offset:44096
	ds_read_b64 v[24:25], v245 offset:44128
	v_fma_f32 v193, |v193|, s19, v4
	v_subrev_f32_e32 v194, 0x42080000, v47
	v_mfma_f32_16x16x32_bf16 v[132:135], v[26:29], v[38:41], v[132:135]
	v_fma_f32 v194, |v194|, s19, v4
	v_subrev_f32_e32 v195, 0x420c0000, v47
	v_mfma_f32_16x16x32_bf16 v[124:127], v[26:29], v[42:45], v[124:127]
	ds_read_b64 v[26:27], v245 offset:46400
	ds_read_b64 v[28:29], v245 offset:46432
	v_fma_f32 v195, |v195|, s19, v4
	v_subrev_f32_e32 v200, 0x42400000, v47
	s_waitcnt lgkmcnt(12)
	v_mfma_f32_16x16x32_bf16 v[120:123], v[30:33], v[38:41], v[120:123]
	v_fma_f32 v200, |v200|, s19, v4
	v_subrev_f32_e32 v201, 0x42440000, v47
	v_mfma_f32_16x16x32_bf16 v[116:119], v[30:33], v[42:45], v[116:119]
	ds_read_b64 v[30:31], v245 offset:48704
	ds_read_b64 v[32:33], v245 offset:48736
	v_fma_f32 v201, |v201|, s19, v4
	v_subrev_f32_e32 v202, 0x42480000, v47
	v_mfma_f32_16x16x32_bf16 v[108:111], v[34:37], v[38:41], v[108:111]
	v_fma_f32 v202, |v202|, s19, v4
	v_subrev_f32_e32 v203, 0x424c0000, v47
	v_mfma_f32_16x16x32_bf16 v[100:103], v[34:37], v[42:45], v[100:103]
	ds_read_b64 v[34:35], v245 offset:51008
	ds_read_b64 v[36:37], v245 offset:51040
	v_fma_f32 v203, |v203|, s19, v4
	v_add_f32_e32 v47, 0xc2800000, v47
	s_waitcnt vmcnt(0)
	ds_write_b128 v251, v[84:87] offset:0
	ds_write_b128 v251, v[88:91] offset:128
	ds_write_b128 v252, v[92:95] offset:53248
	ds_write_b128 v252, v[96:99] offset:53312
	s_sub_i32 s1, s36, 1
	s_add_i32 s0, s4, 3
	s_min_u32 s0, s0, s1
	s_add_i32 s5, s4, 2
	s_min_u32 s5, s5, s1
	s_lshl_b32 s0, s0, 6
	s_lshl_b32 s5, s5, 7
	v_add_u32_e32 v223, s0, v243
	v_min_u32_e32 v223, 0x7ff, v223
	v_lshl_add_u32 v223, v223, 10, v224
	s_add_u32 s26, s24, s5
	s_addc_u32 s27, s25, 0
	global_load_dwordx4 v[84:87], v223, s[22:23]
	global_load_dwordx4 v[88:91], v223, s[22:23] offset:128
	global_load_dwordx4 v[92:95], v46, s[26:27]
	global_load_dwordx4 v[96:99], v46, s[26:27] offset:64
	s_waitcnt lgkmcnt(15)
	v_mfma_f32_16x16x32_bf16 v[184:187], v[6:9], v[0:3], v[184:187]
	v_mfma_f32_16x16x32_bf16 v[188:191], v[6:9], v[230:233], v[188:191]
	v_mfma_f32_16x16x32_bf16 v[180:183], v[10:13], v[0:3], v[180:183]
	v_mfma_f32_16x16x32_bf16 v[176:179], v[10:13], v[230:233], v[176:179]
	s_waitcnt lgkmcnt(12)
	v_mfma_f32_16x16x32_bf16 v[164:167], v[14:17], v[0:3], v[164:167]
	v_mfma_f32_16x16x32_bf16 v[160:163], v[14:17], v[230:233], v[160:163]
	v_mfma_f32_16x16x32_bf16 v[148:151], v[18:21], v[0:3], v[148:151]
	v_mfma_f32_16x16x32_bf16 v[144:147], v[18:21], v[230:233], v[144:147]
	s_waitcnt lgkmcnt(8)
	v_mfma_f32_16x16x32_bf16 v[140:143], v[22:25], v[0:3], v[140:143]
	v_mfma_f32_16x16x32_bf16 v[136:139], v[22:25], v[230:233], v[136:139]
	v_mfma_f32_16x16x32_bf16 v[132:135], v[26:29], v[0:3], v[132:135]
	v_mfma_f32_16x16x32_bf16 v[124:127], v[26:29], v[230:233], v[124:127]
	s_waitcnt lgkmcnt(4)
	v_mfma_f32_16x16x32_bf16 v[120:123], v[30:33], v[0:3], v[120:123]
	v_mfma_f32_16x16x32_bf16 v[116:119], v[30:33], v[230:233], v[116:119]
	v_mfma_f32_16x16x32_bf16 v[108:111], v[34:37], v[0:3], v[108:111]
	v_mfma_f32_16x16x32_bf16 v[100:103], v[34:37], v[230:233], v[100:103]
	s_waitcnt lgkmcnt(0)
	s_barrier
	s_add_i32 s4, s4, 1
; __device__ __forceinline__ void att_qk(const LAS unsigned char* Kb, const bf16x8 (&qf)[2][2], int nst, int j, int qpos, float slope2, int fr, int fq, f32x4 (&sc)[2][4]) {
;     constexpr int KSTR = 272;
; #pragma unroll
;     for (int st = 0; st < 4; ++st) {
;         if (st < nst) {
;             const float d0 = (float)(qpos - (64 * j + 16 * st + 4 * fq));
;             f32x4 s0;
; #pragma unroll
;             for (int e = 0; e < 4; ++e) s0[e] = -slope2 * __builtin_fabsf(d0 - (float)e) - 12.0f;
;             f32x4 s1 = s0;
; #pragma unroll
;             for (int ks = 0; ks < 2; ++ks) {
;                 const bf16x8 k0 = *(const LAS bf16x8*)(Kb + (16 * st + fr) * KSTR + (32 * ks + 8 * fq) * 2);
;                 const bf16x8 k1 = *(const LAS bf16x8*)(Kb + (16 * st + fr) * KSTR + (64 + 32 * ks + 8 * fq) * 2);
;                 s0 = __builtin_amdgcn_mfma_f32_16x16x32_bf16(k0, qf[0][ks], s0, 0, 0, 0);
;                 s1 = __builtin_amdgcn_mfma_f32_16x16x32_bf16(k1, qf[1][ks], s1, 0, 0, 0);
;             }
;             sc[0][st] = s0; sc[1][st] = s1;
;         }
;     }
; }
; __device__ __forceinline__ void att_pv(const LAS unsigned char* Vb, int nst, const f32x4 (&sc)[2][4], f32x4 (&O)[2][8], float& l0, float& l1, int fr, int fq) {
;     constexpr int VSTR = 144;
;     if (nst <= 0) return;
;     unsigned pw[2][4][2];
; #pragma unroll
;     for (int st = 0; st < 4; ++st) {
;         if (st < nst) {
;             float p0[4], p1[4];
; #pragma unroll
;             for (int e = 0; e < 4; ++e) { p0[e] = __builtin_amdgcn_exp2f(sc[0][st][e]); p1[e] = __builtin_amdgcn_exp2f(sc[1][st][e]); l0 += p0[e]; l1 += p1[e]; }
;             pw[0][st][0] = pk2(p0[0], p0[1]); pw[0][st][1] = pk2(p0[2], p0[3]); pw[1][st][0] = pk2(p1[0], p1[1]); pw[1][st][1] = pk2(p1[2], p1[3]);
;         } else { pw[0][st][0] = 0u; pw[0][st][1] = 0u; pw[1][st][0] = 0u; pw[1][st][1] = 0u; }
;     }
; #pragma unroll
;     for (int ks2 = 0; ks2 < 2; ++ks2) {
;         if (ks2 == 0 || nst == 4) {
;             const u32x4 a0 = (u32x4){pw[0][2 * ks2][0], pw[0][2 * ks2][1], pw[0][2 * ks2 + 1][0], pw[0][2 * ks2 + 1][1]};
;             const u32x4 a1 = (u32x4){pw[1][2 * ks2][0], pw[1][2 * ks2][1], pw[1][2 * ks2 + 1][0], pw[1][2 * ks2 + 1][1]};
;             const bf16x8 pf0 = __builtin_bit_cast(bf16x8, a0), pf1 = __builtin_bit_cast(bf16x8, a1);
; #pragma unroll
.Latt_it_o:
	ds_read_b128 v[6:9], v253 offset:128
	ds_read_b128 v[10:13], v253 offset:0
	ds_read_b128 v[14:17], v253 offset:4480
	ds_read_b128 v[18:21], v253 offset:4352
	ds_read_b128 v[22:25], v253 offset:8832
	ds_read_b128 v[26:29], v253 offset:8704
	ds_read_b128 v[30:33], v253 offset:13184
	ds_read_b128 v[34:37], v253 offset:13056
	v_exp_f32_e32 v48, v48
	v_exp_f32_e32 v49, v49
	v_exp_f32_e32 v50, v50
	v_exp_f32_e32 v51, v51
	v_exp_f32_e32 v64, v64
	v_exp_f32_e32 v65, v65
	v_exp_f32_e32 v66, v66
	v_exp_f32_e32 v67, v67
	v_exp_f32_e32 v52, v52
	v_exp_f32_e32 v53, v53
	v_exp_f32_e32 v54, v54
	v_exp_f32_e32 v55, v55
	v_exp_f32_e32 v68, v68
	v_exp_f32_e32 v69, v69
	v_exp_f32_e32 v70, v70
	v_exp_f32_e32 v71, v71
	v_cvt_pk_bf16_f32 v38, v48, v49
	v_cvt_pk_bf16_f32 v39, v50, v51
	v_cvt_pk_bf16_f32 v42, v64, v65
	v_cvt_pk_bf16_f32 v43, v66, v67
	v_pk_add_f32 v[234:235], v[234:235], v[48:49]
	v_pk_add_f32 v[234:235], v[234:235], v[50:51]
	v_pk_add_f32 v[236:237], v[236:237], v[64:65]
	v_pk_add_f32 v[236:237], v[236:237], v[66:67]
	v_cvt_pk_bf16_f32 v40, v52, v53
	v_cvt_pk_bf16_f32 v41, v54, v55
	v_cvt_pk_bf16_f32 v44, v68, v69
	v_cvt_pk_bf16_f32 v45, v70, v71
	v_pk_add_f32 v[234:235], v[234:235], v[52:53]
	v_pk_add_f32 v[234:235], v[234:235], v[54:55]
	v_pk_add_f32 v[236:237], v[236:237], v[68:69]
	v_pk_add_f32 v[236:237], v[236:237], v[70:71]
	s_waitcnt lgkmcnt(6)
	v_mfma_f32_16x16x32_bf16 v[156:159], v[6:9], v[112:115], v[152:155]
	ds_read_b128 v[6:9], v253 offset:192
	v_exp_f32_e32 v56, v56
	v_exp_f32_e32 v57, v57
	v_mfma_f32_16x16x32_bf16 v[152:155], v[10:13], v[80:83], v[152:155]
	ds_read_b128 v[10:13], v253 offset:64
	v_exp_f32_e32 v58, v58
	v_exp_f32_e32 v59, v59
	s_waitcnt lgkmcnt(6)
	v_mfma_f32_16x16x32_bf16 v[172:175], v[14:17], v[112:115], v[168:171]
	ds_read_b128 v[14:17], v253 offset:4544
	v_exp_f32_e32 v72, v72
	v_exp_f32_e32 v73, v73
	v_mfma_f32_16x16x32_bf16 v[168:171], v[18:21], v[80:83], v[168:171]
	ds_read_b128 v[18:21], v253 offset:4416
	v_exp_f32_e32 v74, v74
	v_exp_f32_e32 v75, v75
	s_waitcnt lgkmcnt(6)
	v_mfma_f32_16x16x32_bf16 v[196:199], v[22:25], v[112:115], v[192:195]
	ds_read_b128 v[22:25], v253 offset:8896
	v_exp_f32_e32 v60, v60
	v_exp_f32_e32 v61, v61
	v_mfma_f32_16x16x32_bf16 v[192:195], v[26:29], v[80:83], v[192:195]
	ds_read_b128 v[26:29], v253 offset:8768
	v_exp_f32_e32 v62, v62
	v_exp_f32_e32 v63, v63
	s_waitcnt lgkmcnt(6)
	v_mfma_f32_16x16x32_bf16 v[204:207], v[30:33], v[112:115], v[200:203]
	ds_read_b128 v[30:33], v253 offset:13248
	v_exp_f32_e32 v76, v76
	v_exp_f32_e32 v77, v77
	v_mfma_f32_16x16x32_bf16 v[200:203], v[34:37], v[80:83], v[200:203]
	ds_read_b128 v[34:37], v253 offset:13120
	v_exp_f32_e32 v78, v78
	v_exp_f32_e32 v79, v79
	s_waitcnt lgkmcnt(6)
	v_mfma_f32_16x16x32_bf16 v[156:159], v[6:9], v[128:131], v[156:159]
	ds_read_b64 v[6:7], v246 offset:0
	ds_read_b64 v[8:9], v246 offset:32
	v_cvt_pk_bf16_f32 v0, v56, v57
	v_cvt_pk_bf16_f32 v1, v58, v59
	v_mfma_f32_16x16x32_bf16 v[152:155], v[10:13], v[104:107], v[152:155]
	ds_read_b64 v[10:11], v246 offset:2304
	ds_read_b64 v[12:13], v246 offset:2336
	v_cvt_pk_bf16_f32 v230, v72, v73
	v_cvt_pk_bf16_f32 v231, v74, v75
	s_waitcnt lgkmcnt(8)
	v_mfma_f32_16x16x32_bf16 v[172:175], v[14:17], v[128:131], v[172:175]
	ds_read_b64 v[14:15], v246 offset:4608
	ds_read_b64 v[16:17], v246 offset:4640
	v_pk_add_f32 v[234:235], v[234:235], v[56:57]
	v_pk_add_f32 v[234:235], v[234:235], v[58:59]
	v_mfma_f32_16x16x32_bf16 v[168:171], v[18:21], v[104:107], v[168:171]
	ds_read_b64 v[18:19], v246 offset:6912
	ds_read_b64 v[20:21], v246 offset:6944
	v_pk_add_f32 v[236:237], v[236:237], v[72:73]
	v_pk_add_f32 v[236:237], v[236:237], v[74:75]
	s_waitcnt lgkmcnt(10)
	v_mfma_f32_16x16x32_bf16 v[196:199], v[22:25], v[128:131], v[196:199]
	ds_read_b64 v[22:23], v246 offset:9216
	ds_read_b64 v[24:25], v246 offset:9248
	v_cvt_pk_bf16_f32 v2, v60, v61
	v_cvt_pk_bf16_f32 v3, v62, v63
	v_mfma_f32_16x16x32_bf16 v[192:195], v[26:29], v[104:107], v[192:195]
	ds_read_b64 v[26:27], v246 offset:11520
	ds_read_b64 v[28:29], v246 offset:11552
	v_cvt_pk_bf16_f32 v232, v76, v77
	v_cvt_pk_bf16_f32 v233, v78, v79
	s_waitcnt lgkmcnt(12)
	v_mfma_f32_16x16x32_bf16 v[204:207], v[30:33], v[128:131], v[204:207]
	ds_read_b64 v[30:31], v246 offset:13824
	ds_read_b64 v[32:33], v246 offset:13856
	v_pk_add_f32 v[234:235], v[234:235], v[60:61]
	v_pk_add_f32 v[234:235], v[234:235], v[62:63]
	v_mfma_f32_16x16x32_bf16 v[200:203], v[34:37], v[104:107], v[200:203]
	ds_read_b64 v[34:35], v246 offset:16128
	ds_read_b64 v[36:37], v246 offset:16160
	v_pk_add_f32 v[236:237], v[236:237], v[76:77]
	v_pk_add_f32 v[236:237], v[236:237], v[78:79]
	s_add_i32 s5, s4, 2
	s_cmp_le_u32 s5, s37
	s_cselect_b32 s45, s16, s18
	s_add_i32 s0, s37, 1
	s_cmp_le_u32 s5, s0
	s_cselect_b32 s43, s16, s18
	s_waitcnt lgkmcnt(12)
	v_mfma_f32_16x16x32_bf16 v[184:187], v[6:9], v[38:41], v[184:187]
	v_mov_b32_e32 v4, s43
	v_fma_f32 v48, |v47|, s19, v4
	v_subrev_f32_e32 v49, 0x3f800000, v47
	v_mfma_f32_16x16x32_bf16 v[188:191], v[6:9], v[42:45], v[188:191]
	ds_read_b64 v[6:7], v246 offset:64
	ds_read_b64 v[8:9], v246 offset:96
	v_fma_f32 v49, |v49|, s19, v4
	v_subrev_f32_e32 v50, 0x40000000, v47
	v_fma_f32 v50, |v50|, s19, v4
	v_mfma_f32_16x16x32_bf16 v[180:183], v[10:13], v[38:41], v[180:183]
	v_subrev_f32_e32 v51, 0x40400000, v47
	v_fma_f32 v51, |v51|, s19, v4
	v_mfma_f32_16x16x32_bf16 v[176:179], v[10:13], v[42:45], v[176:179]
	ds_read_b64 v[10:11], v246 offset:2368
	ds_read_b64 v[12:13], v246 offset:2400
	v_mov_b32_e32 v4, s45
	v_subrev_f32_e32 v52, 0x41800000, v47
	s_waitcnt lgkmcnt(12)
; #define LAS __attribute__((address_space(3)))
; __device__ __forceinline__ void att_pv(const LAS unsigned char* Vb, int nst, const f32x4 (&sc)[2][4], f32x4 (&O)[2][8], float& l0, float& l1, int fr, int fq) {
;     constexpr int VSTR = 144;
;     if (nst <= 0) return;
;     unsigned pw[2][4][2];
; #pragma unroll
;     for (int st = 0; st < 4; ++st) {
;         if (st < nst) {
;             float p0[4], p1[4];
; #pragma unroll
;             for (int e = 0; e < 4; ++e) { p0[e] = __builtin_amdgcn_exp2f(sc[0][st][e]); p1[e] = __builtin_amdgcn_exp2f(sc[1][st][e]); l0 += p0[e]; l1 += p1[e]; }
;             pw[0][st][0] = pk2(p0[0], p0[1]); pw[0][st][1] = pk2(p0[2], p0[3]); pw[1][st][0] = pk2(p1[0], p1[1]); pw[1][st][1] = pk2(p1[2], p1[3]);
;         } else { pw[0][st][0] = 0u; pw[0][st][1] = 0u; pw[1][st][0] = 0u; pw[1][st][1] = 0u; }
;     }
; #pragma unroll
;     for (int ks2 = 0; ks2 < 2; ++ks2) {
;         if (ks2 == 0 || nst == 4) {
;             const u32x4 a0 = (u32x4){pw[0][2 * ks2][0], pw[0][2 * ks2][1], pw[0][2 * ks2 + 1][0], pw[0][2 * ks2 + 1][1]};
;             const u32x4 a1 = (u32x4){pw[1][2 * ks2][0], pw[1][2 * ks2][1], pw[1][2 * ks2 + 1][0], pw[1][2 * ks2 + 1][1]};
;             const bf16x8 pf0 = __builtin_bit_cast(bf16x8, a0), pf1 = __builtin_bit_cast(bf16x8, a1);
; #pragma unroll
;             for (int dt = 0; dt < 8; ++dt) {
;                 const LAS unsigned char* vp = Vb + (16 * dt + fr) * VSTR + (32 * ks2 + 4 * fq) * 2;
;                 const u32x2 va = *(const LAS u32x2*)vp, vb2 = *(const LAS u32x2*)(vp + 32);
;                 const bf16x8 vf = __builtin_bit_cast(bf16x8, (u32x4){va.x, va.y, vb2.x, vb2.y});
;                 O[0][dt] = __builtin_amdgcn_mfma_f32_16x16x32_bf16(vf, pf0, O[0][dt], 0, 0, 0);
;                 O[1][dt] = __builtin_amdgcn_mfma_f32_16x16x32_bf16(vf, pf1, O[1][dt], 0, 0, 0);
;             }
;         }
;     }
; }
; __device__ __forceinline__ void attn_phase(const Params& P, LAS unsigned char* lds, int tid, int wid, int lane) {
;     ...
;             if (j + 2 < nt) { if (j + 3 < nt) ATT_LOADK(a, j + 3); ATT_LOADV(a, j + 2); }
;             if (j + 2 < nt) att_qk(lds, qf, ATT_NST(j + 2), j + 2, qpos, slope2, fr, fq, scA);
;             att_pv(lds + VOFF + VBUF, ATT_NST(j + 1), scB, O, l0, l1, fr, fq);
;             if (j + 2 < nt) { if (j + 3 < nt) ATT_WRITEK(a, 1); ATT_WRITEV(a, 0); }
;             ATT_BAR();
	v_mfma_f32_16x16x32_bf16 v[164:167], v[14:17], v[38:41], v[164:167]
	v_fma_f32 v52, |v52|, s19, v4
	v_subrev_f32_e32 v53, 0x41880000, v47
	v_mfma_f32_16x16x32_bf16 v[160:163], v[14:17], v[42:45], v[160:163]
	ds_read_b64 v[14:15], v246 offset:4672
	ds_read_b64 v[16:17], v246 offset:4704
	v_fma_f32 v53, |v53|, s19, v4
	v_subrev_f32_e32 v54, 0x41900000, v47
	v_mfma_f32_16x16x32_bf16 v[148:151], v[18:21], v[38:41], v[148:151]
	v_fma_f32 v54, |v54|, s19, v4
	v_subrev_f32_e32 v55, 0x41980000, v47
	v_mfma_f32_16x16x32_bf16 v[144:147], v[18:21], v[42:45], v[144:147]
	ds_read_b64 v[18:19], v246 offset:6976
	ds_read_b64 v[20:21], v246 offset:7008
	v_fma_f32 v55, |v55|, s19, v4
	v_subrev_f32_e32 v56, 0x42000000, v47
	s_waitcnt lgkmcnt(12)
	v_mfma_f32_16x16x32_bf16 v[140:143], v[22:25], v[38:41], v[140:143]
	v_fma_f32 v56, |v56|, s19, v4
	v_subrev_f32_e32 v57, 0x42040000, v47
	v_mfma_f32_16x16x32_bf16 v[136:139], v[22:25], v[42:45], v[136:139]
	ds_read_b64 v[22:23], v246 offset:9280
	ds_read_b64 v[24:25], v246 offset:9312
	v_fma_f32 v57, |v57|, s19, v4
	v_subrev_f32_e32 v58, 0x42080000, v47
	v_mfma_f32_16x16x32_bf16 v[132:135], v[26:29], v[38:41], v[132:135]
	v_fma_f32 v58, |v58|, s19, v4
	v_subrev_f32_e32 v59, 0x420c0000, v47
	v_mfma_f32_16x16x32_bf16 v[124:127], v[26:29], v[42:45], v[124:127]
	ds_read_b64 v[26:27], v246 offset:11584
	ds_read_b64 v[28:29], v246 offset:11616
	v_fma_f32 v59, |v59|, s19, v4
	v_subrev_f32_e32 v60, 0x42400000, v47
	s_waitcnt lgkmcnt(12)
	v_mfma_f32_16x16x32_bf16 v[120:123], v[30:33], v[38:41], v[120:123]
	v_fma_f32 v60, |v60|, s19, v4
	v_subrev_f32_e32 v61, 0x42440000, v47
	v_mfma_f32_16x16x32_bf16 v[116:119], v[30:33], v[42:45], v[116:119]
	ds_read_b64 v[30:31], v246 offset:13888
	ds_read_b64 v[32:33], v246 offset:13920
	v_fma_f32 v61, |v61|, s19, v4
	v_subrev_f32_e32 v62, 0x42480000, v47
	v_mfma_f32_16x16x32_bf16 v[108:111], v[34:37], v[38:41], v[108:111]
	v_fma_f32 v62, |v62|, s19, v4
	v_subrev_f32_e32 v63, 0x424c0000, v47
	v_mfma_f32_16x16x32_bf16 v[100:103], v[34:37], v[42:45], v[100:103]
	ds_read_b64 v[34:35], v246 offset:16192
	ds_read_b64 v[36:37], v246 offset:16224
	v_fma_f32 v63, |v63|, s19, v4
	v_add_f32_e32 v47, 0xc2800000, v47
	s_waitcnt vmcnt(0)
	ds_write_b128 v251, v[84:87] offset:17408
	ds_write_b128 v251, v[88:91] offset:17536
	ds_write_b128 v252, v[92:95] offset:34816
	ds_write_b128 v252, v[96:99] offset:34880
	s_sub_i32 s1, s36, 1
	s_add_i32 s0, s4, 3
	s_min_u32 s0, s0, s1
	s_add_i32 s5, s4, 2
	s_min_u32 s5, s5, s1
	s_lshl_b32 s0, s0, 6
	s_lshl_b32 s5, s5, 7
	v_add_u32_e32 v223, s0, v243
	v_min_u32_e32 v223, 0x7ff, v223
	v_lshl_add_u32 v223, v223, 10, v224
	s_add_u32 s26, s24, s5
	s_addc_u32 s27, s25, 0
	global_load_dwordx4 v[84:87], v223, s[22:23]
	global_load_dwordx4 v[88:91], v223, s[22:23] offset:128
	global_load_dwordx4 v[92:95], v46, s[26:27]
	global_load_dwordx4 v[96:99], v46, s[26:27] offset:64
	s_waitcnt lgkmcnt(15)
	v_mfma_f32_16x16x32_bf16 v[184:187], v[6:9], v[0:3], v[184:187]
	v_mfma_f32_16x16x32_bf16 v[188:191], v[6:9], v[230:233], v[188:191]
	v_mfma_f32_16x16x32_bf16 v[180:183], v[10:13], v[0:3], v[180:183]
	v_mfma_f32_16x16x32_bf16 v[176:179], v[10:13], v[230:233], v[176:179]
	s_waitcnt lgkmcnt(12)
	v_mfma_f32_16x16x32_bf16 v[164:167], v[14:17], v[0:3], v[164:167]
	v_mfma_f32_16x16x32_bf16 v[160:163], v[14:17], v[230:233], v[160:163]
	v_mfma_f32_16x16x32_bf16 v[148:151], v[18:21], v[0:3], v[148:151]
	v_mfma_f32_16x16x32_bf16 v[144:147], v[18:21], v[230:233], v[144:147]
	s_waitcnt lgkmcnt(8)
	v_mfma_f32_16x16x32_bf16 v[140:143], v[22:25], v[0:3], v[140:143]
	v_mfma_f32_16x16x32_bf16 v[136:139], v[22:25], v[230:233], v[136:139]
	v_mfma_f32_16x16x32_bf16 v[132:135], v[26:29], v[0:3], v[132:135]
	v_mfma_f32_16x16x32_bf16 v[124:127], v[26:29], v[230:233], v[124:127]
	s_waitcnt lgkmcnt(4)
	v_mfma_f32_16x16x32_bf16 v[120:123], v[30:33], v[0:3], v[120:123]
	v_mfma_f32_16x16x32_bf16 v[116:119], v[30:33], v[230:233], v[116:119]
	v_mfma_f32_16x16x32_bf16 v[108:111], v[34:37], v[0:3], v[108:111]
	v_mfma_f32_16x16x32_bf16 v[100:103], v[34:37], v[230:233], v[100:103]
	s_waitcnt lgkmcnt(0)
	s_barrier
	s_add_i32 s4, s4, 1
	s_branch .Latt_top
; #define LAS __attribute__((address_space(3)))
; __device__ __forceinline__ unsigned pk2(float lo, float hi) { return pg8::cvt_pk_bf16(lo, hi); }
; __device__ __forceinline__ void att_pv(const LAS unsigned char* Vb, int nst, const f32x4 (&sc)[2][4], f32x4 (&O)[2][8], float& l0, float& l1, int fr, int fq) {
;     constexpr int VSTR = 144;
;     if (nst <= 0) return;
;     unsigned pw[2][4][2];
; #pragma unroll
;     for (int st = 0; st < 4; ++st) {
;         if (st < nst) {
;             float p0[4], p1[4];
; #pragma unroll
;             for (int e = 0; e < 4; ++e) { p0[e] = __builtin_amdgcn_exp2f(sc[0][st][e]); p1[e] = __builtin_amdgcn_exp2f(sc[1][st][e]); l0 += p0[e]; l1 += p1[e]; }
;             pw[0][st][0] = pk2(p0[0], p0[1]); pw[0][st][1] = pk2(p0[2], p0[3]); pw[1][st][0] = pk2(p1[0], p1[1]); pw[1][st][1] = pk2(p1[2], p1[3]);
;         } else { pw[0][st][0] = 0u; pw[0][st][1] = 0u; pw[1][st][0] = 0u; pw[1][st][1] = 0u; }
;     }
; #pragma unroll
;     for (int ks2 = 0; ks2 < 2; ++ks2) {
;         if (ks2 == 0 || nst == 4) {
;             const u32x4 a0 = (u32x4){pw[0][2 * ks2][0], pw[0][2 * ks2][1], pw[0][2 * ks2 + 1][0], pw[0][2 * ks2 + 1][1]};
;             const u32x4 a1 = (u32x4){pw[1][2 * ks2][0], pw[1][2 * ks2][1], pw[1][2 * ks2 + 1][0], pw[1][2 * ks2 + 1][1]};
;             const bf16x8 pf0 = __builtin_bit_cast(bf16x8, a0), pf1 = __builtin_bit_cast(bf16x8, a1);
; #pragma unroll
;             for (int dt = 0; dt < 8; ++dt) {
;                 const LAS unsigned char* vp = Vb + (16 * dt + fr) * VSTR + (32 * ks2 + 4 * fq) * 2;
;                 const u32x2 va = *(const LAS u32x2*)vp, vb2 = *(const LAS u32x2*)(vp + 32);
;                 const bf16x8 vf = __builtin_bit_cast(bf16x8, (u32x4){va.x, va.y, vb2.x, vb2.y});
;                 O[0][dt] = __builtin_amdgcn_mfma_f32_16x16x32_bf16(vf, pf0, O[0][dt], 0, 0, 0);
;                 O[1][dt] = __builtin_amdgcn_mfma_f32_16x16x32_bf16(vf, pf1, O[1][dt], 0, 0, 0);
;             }
;         }
;     }
; }
; __device__ __forceinline__ void attn_phase(const Params& P, LAS unsigned char* lds, int tid, int wid, int lane) {
;     ...
;             att_pv(lds + VOFF, ATT_NST(j), scA, O, l0, l1, fr, fq);
;             if (j + 1 < nt) { if (j + 2 < nt) ATT_WRITEK(a, 0); ATT_WRITEV(a, 1); }
;             ATT_BAR();
;             if (j + 1 >= nt) break;
.Latt_it_l:
	ds_read_b64 v[6:7], v245 offset:34816
	ds_read_b64 v[8:9], v245 offset:34848
	ds_read_b64 v[10:11], v245 offset:37120
	ds_read_b64 v[12:13], v245 offset:37152
	ds_read_b64 v[14:15], v245 offset:39424
	ds_read_b64 v[16:17], v245 offset:39456
	ds_read_b64 v[18:19], v245 offset:41728
	ds_read_b64 v[20:21], v245 offset:41760
	ds_read_b64 v[22:23], v245 offset:44032
	ds_read_b64 v[24:25], v245 offset:44064
	ds_read_b64 v[26:27], v245 offset:46336
	ds_read_b64 v[28:29], v245 offset:46368
	ds_read_b64 v[30:31], v245 offset:48640
	ds_read_b64 v[32:33], v245 offset:48672
	ds_read_b64 v[34:35], v245 offset:50944
	ds_read_b64 v[36:37], v245 offset:50976
	v_exp_f32_e32 v152, v152
	v_exp_f32_e32 v153, v153
	v_exp_f32_e32 v154, v154
	v_exp_f32_e32 v155, v155
	v_exp_f32_e32 v156, v156
	v_exp_f32_e32 v157, v157
	v_exp_f32_e32 v158, v158
	v_exp_f32_e32 v159, v159
	v_exp_f32_e32 v168, v168
	v_exp_f32_e32 v169, v169
	v_exp_f32_e32 v170, v170
	v_exp_f32_e32 v171, v171
	v_exp_f32_e32 v172, v172
	v_exp_f32_e32 v173, v173
	v_exp_f32_e32 v174, v174
	v_exp_f32_e32 v175, v175
	v_cvt_pk_bf16_f32 v38, v152, v153
	v_cvt_pk_bf16_f32 v39, v154, v155
	v_cvt_pk_bf16_f32 v42, v156, v157
	v_cvt_pk_bf16_f32 v43, v158, v159
	v_pk_add_f32 v[234:235], v[234:235], v[152:153]
	v_pk_add_f32 v[234:235], v[234:235], v[154:155]
	v_pk_add_f32 v[236:237], v[236:237], v[156:157]
	v_pk_add_f32 v[236:237], v[236:237], v[158:159]
	v_cvt_pk_bf16_f32 v40, v168, v169
	v_cvt_pk_bf16_f32 v41, v170, v171
	v_cvt_pk_bf16_f32 v44, v172, v173
	v_cvt_pk_bf16_f32 v45, v174, v175
	v_pk_add_f32 v[234:235], v[234:235], v[168:169]
	v_pk_add_f32 v[234:235], v[234:235], v[170:171]
	v_pk_add_f32 v[236:237], v[236:237], v[172:173]
	v_pk_add_f32 v[236:237], v[236:237], v[174:175]
	s_waitcnt lgkmcnt(12)
	v_mfma_f32_16x16x32_bf16 v[184:187], v[6:9], v[38:41], v[184:187]
	v_exp_f32_e32 v192, v192
	v_exp_f32_e32 v193, v193
	v_mfma_f32_16x16x32_bf16 v[188:191], v[6:9], v[42:45], v[188:191]
	ds_read_b64 v[6:7], v245 offset:34880
	ds_read_b64 v[8:9], v245 offset:34912
	v_exp_f32_e32 v194, v194
	v_exp_f32_e32 v195, v195
	v_mfma_f32_16x16x32_bf16 v[180:183], v[10:13], v[38:41], v[180:183]
	v_exp_f32_e32 v196, v196
	v_exp_f32_e32 v197, v197
	v_mfma_f32_16x16x32_bf16 v[176:179], v[10:13], v[42:45], v[176:179]
	ds_read_b64 v[10:11], v245 offset:37184
	ds_read_b64 v[12:13], v245 offset:37216
	v_exp_f32_e32 v198, v198
	v_exp_f32_e32 v199, v199
	s_waitcnt lgkmcnt(12)
	v_mfma_f32_16x16x32_bf16 v[164:167], v[14:17], v[38:41], v[164:167]
	v_exp_f32_e32 v200, v200
	v_exp_f32_e32 v201, v201
	v_mfma_f32_16x16x32_bf16 v[160:163], v[14:17], v[42:45], v[160:163]
	ds_read_b64 v[14:15], v245 offset:39488
	ds_read_b64 v[16:17], v245 offset:39520
	v_exp_f32_e32 v202, v202
	v_exp_f32_e32 v203, v203
	v_mfma_f32_16x16x32_bf16 v[148:151], v[18:21], v[38:41], v[148:151]
	v_exp_f32_e32 v204, v204
	v_exp_f32_e32 v205, v205
	v_mfma_f32_16x16x32_bf16 v[144:147], v[18:21], v[42:45], v[144:147]
	ds_read_b64 v[18:19], v245 offset:41792
	ds_read_b64 v[20:21], v245 offset:41824
	v_exp_f32_e32 v206, v206
	v_exp_f32_e32 v207, v207
	s_waitcnt lgkmcnt(12)
	v_mfma_f32_16x16x32_bf16 v[140:143], v[22:25], v[38:41], v[140:143]
	v_cvt_pk_bf16_f32 v0, v192, v193
	v_cvt_pk_bf16_f32 v1, v194, v195
	v_mfma_f32_16x16x32_bf16 v[136:139], v[22:25], v[42:45], v[136:139]
	ds_read_b64 v[22:23], v245 offset:44096
	ds_read_b64 v[24:25], v245 offset:44128
	v_cvt_pk_bf16_f32 v230, v196, v197
	v_cvt_pk_bf16_f32 v231, v198, v199
	v_mfma_f32_16x16x32_bf16 v[132:135], v[26:29], v[38:41], v[132:135]
	v_pk_add_f32 v[234:235], v[234:235], v[192:193]
	v_pk_add_f32 v[234:235], v[234:235], v[194:195]
	v_mfma_f32_16x16x32_bf16 v[124:127], v[26:29], v[42:45], v[124:127]
	ds_read_b64 v[26:27], v245 offset:46400
	ds_read_b64 v[28:29], v245 offset:46432
	v_pk_add_f32 v[236:237], v[236:237], v[196:197]
	v_pk_add_f32 v[236:237], v[236:237], v[198:199]
	s_waitcnt lgkmcnt(12)
	v_mfma_f32_16x16x32_bf16 v[120:123], v[30:33], v[38:41], v[120:123]
	v_cvt_pk_bf16_f32 v2, v200, v201
	v_cvt_pk_bf16_f32 v3, v202, v203
	v_mfma_f32_16x16x32_bf16 v[116:119], v[30:33], v[42:45], v[116:119]
	ds_read_b64 v[30:31], v245 offset:48704
	ds_read_b64 v[32:33], v245 offset:48736
	v_cvt_pk_bf16_f32 v232, v204, v205
	v_cvt_pk_bf16_f32 v233, v206, v207
	v_mfma_f32_16x16x32_bf16 v[108:111], v[34:37], v[38:41], v[108:111]
	v_pk_add_f32 v[234:235], v[234:235], v[200:201]
	v_pk_add_f32 v[234:235], v[234:235], v[202:203]
	v_mfma_f32_16x16x32_bf16 v[100:103], v[34:37], v[42:45], v[100:103]
	ds_read_b64 v[34:35], v245 offset:51008
	ds_read_b64 v[36:37], v245 offset:51040
	v_pk_add_f32 v[236:237], v[236:237], v[204:205]
	v_pk_add_f32 v[236:237], v[236:237], v[206:207]
	s_waitcnt lgkmcnt(12)
	v_mfma_f32_16x16x32_bf16 v[184:187], v[6:9], v[0:3], v[184:187]
	v_mfma_f32_16x16x32_bf16 v[188:191], v[6:9], v[230:233], v[188:191]
	v_mfma_f32_16x16x32_bf16 v[180:183], v[10:13], v[0:3], v[180:183]
	v_mfma_f32_16x16x32_bf16 v[176:179], v[10:13], v[230:233], v[176:179]
	s_waitcnt lgkmcnt(8)
	v_mfma_f32_16x16x32_bf16 v[164:167], v[14:17], v[0:3], v[164:167]
	v_mfma_f32_16x16x32_bf16 v[160:163], v[14:17], v[230:233], v[160:163]
	v_mfma_f32_16x16x32_bf16 v[148:151], v[18:21], v[0:3], v[148:151]
	v_mfma_f32_16x16x32_bf16 v[144:147], v[18:21], v[230:233], v[144:147]
	s_waitcnt lgkmcnt(4)
	v_mfma_f32_16x16x32_bf16 v[140:143], v[22:25], v[0:3], v[140:143]
	v_mfma_f32_16x16x32_bf16 v[136:139], v[22:25], v[230:233], v[136:139]
	v_mfma_f32_16x16x32_bf16 v[132:135], v[26:29], v[0:3], v[132:135]
	v_mfma_f32_16x16x32_bf16 v[124:127], v[26:29], v[230:233], v[124:127]
	s_waitcnt lgkmcnt(0)
	v_mfma_f32_16x16x32_bf16 v[120:123], v[30:33], v[0:3], v[120:123]
	v_mfma_f32_16x16x32_bf16 v[116:119], v[30:33], v[230:233], v[116:119]
	v_mfma_f32_16x16x32_bf16 v[108:111], v[34:37], v[0:3], v[108:111]
	v_mfma_f32_16x16x32_bf16 v[100:103], v[34:37], v[230:233], v[100:103]
.Latt_exit:
	s_waitcnt vmcnt(0)
	v_add_f32_e32 v234, v234, v235
	v_add_f32_e32 v235, v236, v237
	v_mov_b32_e32 v5, 0
	s_nop 7
	s_nop 7
	s_branch .LBB0_616
